# scan stage C: next-step kk prefetch, S*w multiplies overlapped with the cross-lane allreduce
# baseline (speedup 1.0000x reference)
.LBB0_534:
	s_or_b64 exec, exec, s[22:23]
	s_waitcnt lgkmcnt(0)
	s_barrier
	s_and_saveexec_b64 s[16:17], s[18:19]
	s_cbranch_execz .LBB0_497
	s_and_saveexec_b64 s[22:23], s[4:5]
	s_setprio 2
	s_or_b64 exec, exec, s[22:23]
	s_mov_b32 s2, 0
	s_mov_b32 s3, s31
	v_mov_b32_e32 v247, v185
	v_and_b32_e32 v196, 0xc0, v174
	v_add_u32_e32 v196, v196, v185
	ds_read_b128 v[128:131], v196 offset:20480
	ds_read_b128 v[132:135], v196 offset:20496
	ds_read_b128 v[136:139], v196 offset:20512
	ds_read_b128 v[140:143], v196 offset:20528
	s_branch .LBB0_539

.LBB0_539:
	v_and_b32_e32 v196, 0xc0, v174
	v_and_b32_e32 v152, 60, v174
	v_add_u32_e32 v196, v196, v247
	v_add_u32_e32 v152, v152, v247
	v_mov_b32_e32 v144, 0
	v_mov_b32_e32 v146, 0
	v_mov_b32_e32 v148, 0
	v_mov_b32_e32 v150, 0
	s_and_saveexec_b64 s[22:23], s[4:5]
	ds_read_b32 v144, v152 offset:8192
	ds_read_b32 v146, v152 offset:8256
	ds_read_b32 v148, v152 offset:8320
	ds_read_b32 v150, v152 offset:8384
	s_or_b64 exec, exec, s[22:23]
	ds_read_b128 v[80:83], v196 offset:12288
	ds_read_b128 v[84:87], v196 offset:12304
	ds_read_b128 v[88:91], v196 offset:12320
	ds_read_b128 v[92:95], v196 offset:12336
	s_waitcnt lgkmcnt(4)
	v_pk_mul_f32 v[152:153], v[0:1], v[128:129]
	v_pk_mul_f32 v[154:155], v[16:17], v[128:129]
	v_pk_mul_f32 v[156:157], v[32:33], v[128:129]
	v_pk_mul_f32 v[158:159], v[48:49], v[128:129]
	ds_read_b128 v[96:99], v196 offset:16384
	ds_read_b128 v[100:103], v196 offset:16400
	v_pk_fma_f32 v[152:153], v[2:3], v[130:131], v[152:153]
	v_pk_fma_f32 v[154:155], v[18:19], v[130:131], v[154:155]
	v_pk_fma_f32 v[156:157], v[34:35], v[130:131], v[156:157]
	v_pk_fma_f32 v[158:159], v[50:51], v[130:131], v[158:159]
	ds_read_b128 v[104:107], v196 offset:16416
	ds_read_b128 v[108:111], v196 offset:16432
	v_pk_fma_f32 v[152:153], v[4:5], v[132:133], v[152:153]
	v_pk_fma_f32 v[154:155], v[20:21], v[132:133], v[154:155]
	v_pk_fma_f32 v[156:157], v[36:37], v[132:133], v[156:157]
	v_pk_fma_f32 v[158:159], v[52:53], v[132:133], v[158:159]
	ds_read_b128 v[112:115], v196 offset:4096
	ds_read_b128 v[116:119], v196 offset:4112
	v_pk_fma_f32 v[152:153], v[6:7], v[134:135], v[152:153]
	v_pk_fma_f32 v[154:155], v[22:23], v[134:135], v[154:155]
	v_pk_fma_f32 v[156:157], v[38:39], v[134:135], v[156:157]
	v_pk_fma_f32 v[158:159], v[54:55], v[134:135], v[158:159]
	ds_read_b128 v[120:123], v196 offset:4128
	ds_read_b128 v[124:127], v196 offset:4144
	v_pk_fma_f32 v[152:153], v[8:9], v[136:137], v[152:153]
	v_pk_fma_f32 v[154:155], v[24:25], v[136:137], v[154:155]
	v_pk_fma_f32 v[156:157], v[40:41], v[136:137], v[156:157]
	v_pk_fma_f32 v[158:159], v[56:57], v[136:137], v[158:159]
	ds_read_b128 v[64:67], v196 offset:0
	ds_read_b128 v[68:71], v196 offset:16
	v_pk_fma_f32 v[152:153], v[10:11], v[138:139], v[152:153]
	v_pk_fma_f32 v[154:155], v[26:27], v[138:139], v[154:155]
	v_pk_fma_f32 v[156:157], v[42:43], v[138:139], v[156:157]
	v_pk_fma_f32 v[158:159], v[58:59], v[138:139], v[158:159]
	ds_read_b128 v[72:75], v196 offset:32
	ds_read_b128 v[76:79], v196 offset:48
	v_pk_fma_f32 v[152:153], v[12:13], v[140:141], v[152:153]
	v_pk_fma_f32 v[154:155], v[28:29], v[140:141], v[154:155]
	v_pk_fma_f32 v[156:157], v[44:45], v[140:141], v[156:157]
	v_pk_fma_f32 v[158:159], v[60:61], v[140:141], v[158:159]
	v_pk_fma_f32 v[152:153], v[14:15], v[142:143], v[152:153]
	v_pk_fma_f32 v[154:155], v[30:31], v[142:143], v[154:155]
	v_pk_fma_f32 v[156:157], v[46:47], v[142:143], v[156:157]
	v_pk_fma_f32 v[158:159], v[62:63], v[142:143], v[158:159]
	ds_read_b128 v[128:131], v196 offset:20736
	ds_read_b128 v[132:135], v196 offset:20752
	ds_read_b128 v[136:139], v196 offset:20768
	ds_read_b128 v[140:143], v196 offset:20784
	v_add_f32_e32 v152, v152, v153
	v_add_f32_e32 v154, v154, v155
	v_add_f32_e32 v156, v156, v157
	v_add_f32_e32 v158, v158, v159
	s_nop 0
	v_permlane16_swap_b32_e32 v152, v154
	v_permlane16_swap_b32_e32 v156, v158
	v_add_f32_e32 v152, v152, v154
	v_add_f32_e32 v156, v156, v158
	s_waitcnt lgkmcnt(12)
	v_pk_mul_f32 v[0:1], v[0:1], v[80:81]
	v_pk_mul_f32 v[16:17], v[16:17], v[80:81]
	v_permlane32_swap_b32_e32 v152, v156
	v_add_f32_e32 v152, v152, v156
	v_mov_b32_e32 v154, v152
	v_pk_mul_f32 v[32:33], v[32:33], v[80:81]
	v_pk_mul_f32 v[48:49], v[48:49], v[80:81]
	v_permlane16_swap_b32_e32 v152, v154
	v_mov_b32_e32 v156, v152
	v_mov_b32_e32 v158, v154
	v_pk_mul_f32 v[2:3], v[2:3], v[82:83]
	v_pk_mul_f32 v[18:19], v[18:19], v[82:83]
	v_permlane32_swap_b32_e32 v152, v156
	v_permlane32_swap_b32_e32 v154, v158
	s_waitcnt lgkmcnt(0)
	v_pk_mul_f32 v[34:35], v[34:35], v[82:83]
	v_pk_mul_f32 v[50:51], v[50:51], v[82:83]
	v_pk_mul_f32 v[4:5], v[4:5], v[84:85]
	v_pk_mul_f32 v[20:21], v[20:21], v[84:85]
	v_pk_mul_f32 v[36:37], v[36:37], v[84:85]
	v_pk_mul_f32 v[52:53], v[52:53], v[84:85]
	v_pk_mul_f32 v[6:7], v[6:7], v[86:87]
	v_pk_mul_f32 v[22:23], v[22:23], v[86:87]
	v_pk_mul_f32 v[38:39], v[38:39], v[86:87]
	v_pk_mul_f32 v[54:55], v[54:55], v[86:87]
	v_pk_mul_f32 v[8:9], v[8:9], v[88:89]
	v_pk_mul_f32 v[24:25], v[24:25], v[88:89]
	v_pk_mul_f32 v[40:41], v[40:41], v[88:89]
	v_pk_mul_f32 v[56:57], v[56:57], v[88:89]
	v_pk_mul_f32 v[10:11], v[10:11], v[90:91]
	v_pk_mul_f32 v[26:27], v[26:27], v[90:91]
	v_pk_mul_f32 v[42:43], v[42:43], v[90:91]
	v_pk_mul_f32 v[58:59], v[58:59], v[90:91]
	v_pk_mul_f32 v[12:13], v[12:13], v[92:93]
	v_pk_mul_f32 v[28:29], v[28:29], v[92:93]
	v_pk_mul_f32 v[44:45], v[44:45], v[92:93]
	v_pk_mul_f32 v[60:61], v[60:61], v[92:93]
	v_pk_mul_f32 v[14:15], v[14:15], v[94:95]
	v_pk_mul_f32 v[30:31], v[30:31], v[94:95]
	v_pk_mul_f32 v[46:47], v[46:47], v[94:95]
	v_pk_mul_f32 v[62:63], v[62:63], v[94:95]
	s_cmp_eq_u64 s[4:5], 0
	s_cbranch_scc1 .Lscan_T
	v_pk_fma_f32 v[0:1], v[152:153], v[96:97], v[0:1] op_sel_hi:[0,1,1] neg_lo:[1,0,0] neg_hi:[1,0,0]
	v_pk_fma_f32 v[16:17], v[154:155], v[96:97], v[16:17] op_sel_hi:[0,1,1] neg_lo:[1,0,0] neg_hi:[1,0,0]
	v_pk_fma_f32 v[32:33], v[156:157], v[96:97], v[32:33] op_sel_hi:[0,1,1] neg_lo:[1,0,0] neg_hi:[1,0,0]
	v_pk_fma_f32 v[48:49], v[158:159], v[96:97], v[48:49] op_sel_hi:[0,1,1] neg_lo:[1,0,0] neg_hi:[1,0,0]
	v_pk_fma_f32 v[0:1], v[144:145], v[112:113], v[0:1] op_sel_hi:[0,1,1]
	v_pk_fma_f32 v[16:17], v[146:147], v[112:113], v[16:17] op_sel_hi:[0,1,1]
	v_pk_fma_f32 v[32:33], v[148:149], v[112:113], v[32:33] op_sel_hi:[0,1,1]
	v_pk_fma_f32 v[48:49], v[150:151], v[112:113], v[48:49] op_sel_hi:[0,1,1]
	v_pk_mul_f32 v[230:231], v[0:1], v[64:65]
	v_pk_mul_f32 v[232:233], v[16:17], v[64:65]
	v_pk_mul_f32 v[248:249], v[32:33], v[64:65]
	v_pk_mul_f32 v[250:251], v[48:49], v[64:65]
	v_pk_fma_f32 v[2:3], v[152:153], v[98:99], v[2:3] op_sel_hi:[0,1,1] neg_lo:[1,0,0] neg_hi:[1,0,0]
	v_pk_fma_f32 v[18:19], v[154:155], v[98:99], v[18:19] op_sel_hi:[0,1,1] neg_lo:[1,0,0] neg_hi:[1,0,0]
	v_pk_fma_f32 v[34:35], v[156:157], v[98:99], v[34:35] op_sel_hi:[0,1,1] neg_lo:[1,0,0] neg_hi:[1,0,0]
	v_pk_fma_f32 v[50:51], v[158:159], v[98:99], v[50:51] op_sel_hi:[0,1,1] neg_lo:[1,0,0] neg_hi:[1,0,0]
	v_pk_fma_f32 v[2:3], v[144:145], v[114:115], v[2:3] op_sel_hi:[0,1,1]
	v_pk_fma_f32 v[18:19], v[146:147], v[114:115], v[18:19] op_sel_hi:[0,1,1]
	v_pk_fma_f32 v[34:35], v[148:149], v[114:115], v[34:35] op_sel_hi:[0,1,1]
	v_pk_fma_f32 v[50:51], v[150:151], v[114:115], v[50:51] op_sel_hi:[0,1,1]
	v_pk_fma_f32 v[230:231], v[2:3], v[66:67], v[230:231]
	v_pk_fma_f32 v[232:233], v[18:19], v[66:67], v[232:233]
	v_pk_fma_f32 v[248:249], v[34:35], v[66:67], v[248:249]
	v_pk_fma_f32 v[250:251], v[50:51], v[66:67], v[250:251]
	v_pk_fma_f32 v[4:5], v[152:153], v[100:101], v[4:5] op_sel_hi:[0,1,1] neg_lo:[1,0,0] neg_hi:[1,0,0]
	v_pk_fma_f32 v[20:21], v[154:155], v[100:101], v[20:21] op_sel_hi:[0,1,1] neg_lo:[1,0,0] neg_hi:[1,0,0]
	v_pk_fma_f32 v[36:37], v[156:157], v[100:101], v[36:37] op_sel_hi:[0,1,1] neg_lo:[1,0,0] neg_hi:[1,0,0]
	v_pk_fma_f32 v[52:53], v[158:159], v[100:101], v[52:53] op_sel_hi:[0,1,1] neg_lo:[1,0,0] neg_hi:[1,0,0]
	v_pk_fma_f32 v[4:5], v[144:145], v[116:117], v[4:5] op_sel_hi:[0,1,1]
	v_pk_fma_f32 v[20:21], v[146:147], v[116:117], v[20:21] op_sel_hi:[0,1,1]
	v_pk_fma_f32 v[36:37], v[148:149], v[116:117], v[36:37] op_sel_hi:[0,1,1]
	v_pk_fma_f32 v[52:53], v[150:151], v[116:117], v[52:53] op_sel_hi:[0,1,1]
	v_pk_fma_f32 v[230:231], v[4:5], v[68:69], v[230:231]
	v_pk_fma_f32 v[232:233], v[20:21], v[68:69], v[232:233]
	v_pk_fma_f32 v[248:249], v[36:37], v[68:69], v[248:249]
	v_pk_fma_f32 v[250:251], v[52:53], v[68:69], v[250:251]
	v_pk_fma_f32 v[6:7], v[152:153], v[102:103], v[6:7] op_sel_hi:[0,1,1] neg_lo:[1,0,0] neg_hi:[1,0,0]
	v_pk_fma_f32 v[22:23], v[154:155], v[102:103], v[22:23] op_sel_hi:[0,1,1] neg_lo:[1,0,0] neg_hi:[1,0,0]
	v_pk_fma_f32 v[38:39], v[156:157], v[102:103], v[38:39] op_sel_hi:[0,1,1] neg_lo:[1,0,0] neg_hi:[1,0,0]
	v_pk_fma_f32 v[54:55], v[158:159], v[102:103], v[54:55] op_sel_hi:[0,1,1] neg_lo:[1,0,0] neg_hi:[1,0,0]
	v_pk_fma_f32 v[6:7], v[144:145], v[118:119], v[6:7] op_sel_hi:[0,1,1]
	v_pk_fma_f32 v[22:23], v[146:147], v[118:119], v[22:23] op_sel_hi:[0,1,1]
	v_pk_fma_f32 v[38:39], v[148:149], v[118:119], v[38:39] op_sel_hi:[0,1,1]
	v_pk_fma_f32 v[54:55], v[150:151], v[118:119], v[54:55] op_sel_hi:[0,1,1]
	v_pk_fma_f32 v[230:231], v[6:7], v[70:71], v[230:231]
	v_pk_fma_f32 v[232:233], v[22:23], v[70:71], v[232:233]
	v_pk_fma_f32 v[248:249], v[38:39], v[70:71], v[248:249]
	v_pk_fma_f32 v[250:251], v[54:55], v[70:71], v[250:251]
	v_pk_fma_f32 v[8:9], v[152:153], v[104:105], v[8:9] op_sel_hi:[0,1,1] neg_lo:[1,0,0] neg_hi:[1,0,0]
	v_pk_fma_f32 v[24:25], v[154:155], v[104:105], v[24:25] op_sel_hi:[0,1,1] neg_lo:[1,0,0] neg_hi:[1,0,0]
	v_pk_fma_f32 v[40:41], v[156:157], v[104:105], v[40:41] op_sel_hi:[0,1,1] neg_lo:[1,0,0] neg_hi:[1,0,0]
	v_pk_fma_f32 v[56:57], v[158:159], v[104:105], v[56:57] op_sel_hi:[0,1,1] neg_lo:[1,0,0] neg_hi:[1,0,0]
	v_pk_fma_f32 v[8:9], v[144:145], v[120:121], v[8:9] op_sel_hi:[0,1,1]
	v_pk_fma_f32 v[24:25], v[146:147], v[120:121], v[24:25] op_sel_hi:[0,1,1]
	v_pk_fma_f32 v[40:41], v[148:149], v[120:121], v[40:41] op_sel_hi:[0,1,1]
	v_pk_fma_f32 v[56:57], v[150:151], v[120:121], v[56:57] op_sel_hi:[0,1,1]
	v_pk_fma_f32 v[230:231], v[8:9], v[72:73], v[230:231]
	v_pk_fma_f32 v[232:233], v[24:25], v[72:73], v[232:233]
	v_pk_fma_f32 v[248:249], v[40:41], v[72:73], v[248:249]
	v_pk_fma_f32 v[250:251], v[56:57], v[72:73], v[250:251]
	v_pk_fma_f32 v[10:11], v[152:153], v[106:107], v[10:11] op_sel_hi:[0,1,1] neg_lo:[1,0,0] neg_hi:[1,0,0]
	v_pk_fma_f32 v[26:27], v[154:155], v[106:107], v[26:27] op_sel_hi:[0,1,1] neg_lo:[1,0,0] neg_hi:[1,0,0]
	v_pk_fma_f32 v[42:43], v[156:157], v[106:107], v[42:43] op_sel_hi:[0,1,1] neg_lo:[1,0,0] neg_hi:[1,0,0]
	v_pk_fma_f32 v[58:59], v[158:159], v[106:107], v[58:59] op_sel_hi:[0,1,1] neg_lo:[1,0,0] neg_hi:[1,0,0]
	v_pk_fma_f32 v[10:11], v[144:145], v[122:123], v[10:11] op_sel_hi:[0,1,1]
	v_pk_fma_f32 v[26:27], v[146:147], v[122:123], v[26:27] op_sel_hi:[0,1,1]
	v_pk_fma_f32 v[42:43], v[148:149], v[122:123], v[42:43] op_sel_hi:[0,1,1]
	v_pk_fma_f32 v[58:59], v[150:151], v[122:123], v[58:59] op_sel_hi:[0,1,1]
	v_pk_fma_f32 v[230:231], v[10:11], v[74:75], v[230:231]
	v_pk_fma_f32 v[232:233], v[26:27], v[74:75], v[232:233]
	v_pk_fma_f32 v[248:249], v[42:43], v[74:75], v[248:249]
	v_pk_fma_f32 v[250:251], v[58:59], v[74:75], v[250:251]
	v_pk_fma_f32 v[12:13], v[152:153], v[108:109], v[12:13] op_sel_hi:[0,1,1] neg_lo:[1,0,0] neg_hi:[1,0,0]
	v_pk_fma_f32 v[28:29], v[154:155], v[108:109], v[28:29] op_sel_hi:[0,1,1] neg_lo:[1,0,0] neg_hi:[1,0,0]
	v_pk_fma_f32 v[44:45], v[156:157], v[108:109], v[44:45] op_sel_hi:[0,1,1] neg_lo:[1,0,0] neg_hi:[1,0,0]
	v_pk_fma_f32 v[60:61], v[158:159], v[108:109], v[60:61] op_sel_hi:[0,1,1] neg_lo:[1,0,0] neg_hi:[1,0,0]
	v_pk_fma_f32 v[12:13], v[144:145], v[124:125], v[12:13] op_sel_hi:[0,1,1]
	v_pk_fma_f32 v[28:29], v[146:147], v[124:125], v[28:29] op_sel_hi:[0,1,1]
	v_pk_fma_f32 v[44:45], v[148:149], v[124:125], v[44:45] op_sel_hi:[0,1,1]
	v_pk_fma_f32 v[60:61], v[150:151], v[124:125], v[60:61] op_sel_hi:[0,1,1]
	v_pk_fma_f32 v[230:231], v[12:13], v[76:77], v[230:231]
	v_pk_fma_f32 v[232:233], v[28:29], v[76:77], v[232:233]
	v_pk_fma_f32 v[248:249], v[44:45], v[76:77], v[248:249]
	v_pk_fma_f32 v[250:251], v[60:61], v[76:77], v[250:251]
	v_pk_fma_f32 v[14:15], v[152:153], v[110:111], v[14:15] op_sel_hi:[0,1,1] neg_lo:[1,0,0] neg_hi:[1,0,0]
	v_pk_fma_f32 v[30:31], v[154:155], v[110:111], v[30:31] op_sel_hi:[0,1,1] neg_lo:[1,0,0] neg_hi:[1,0,0]
	v_pk_fma_f32 v[46:47], v[156:157], v[110:111], v[46:47] op_sel_hi:[0,1,1] neg_lo:[1,0,0] neg_hi:[1,0,0]
	v_pk_fma_f32 v[62:63], v[158:159], v[110:111], v[62:63] op_sel_hi:[0,1,1] neg_lo:[1,0,0] neg_hi:[1,0,0]
	v_pk_fma_f32 v[14:15], v[144:145], v[126:127], v[14:15] op_sel_hi:[0,1,1]
	v_pk_fma_f32 v[30:31], v[146:147], v[126:127], v[30:31] op_sel_hi:[0,1,1]
	v_pk_fma_f32 v[46:47], v[148:149], v[126:127], v[46:47] op_sel_hi:[0,1,1]
	v_pk_fma_f32 v[62:63], v[150:151], v[126:127], v[62:63] op_sel_hi:[0,1,1]
	v_pk_fma_f32 v[230:231], v[14:15], v[78:79], v[230:231]
	v_pk_fma_f32 v[232:233], v[30:31], v[78:79], v[232:233]
	v_pk_fma_f32 v[248:249], v[46:47], v[78:79], v[248:249]
	v_pk_fma_f32 v[250:251], v[62:63], v[78:79], v[250:251]
	s_branch .Lscan_join
.Lscan_T:
	v_pk_fma_f32 v[0:1], v[152:153], v[96:97], v[0:1] op_sel_hi:[0,1,1] neg_lo:[1,0,0] neg_hi:[1,0,0]
	v_pk_fma_f32 v[16:17], v[154:155], v[96:97], v[16:17] op_sel_hi:[0,1,1] neg_lo:[1,0,0] neg_hi:[1,0,0]
	v_pk_fma_f32 v[32:33], v[156:157], v[96:97], v[32:33] op_sel_hi:[0,1,1] neg_lo:[1,0,0] neg_hi:[1,0,0]
	v_pk_fma_f32 v[48:49], v[158:159], v[96:97], v[48:49] op_sel_hi:[0,1,1] neg_lo:[1,0,0] neg_hi:[1,0,0]
	v_pk_mul_f32 v[230:231], v[0:1], v[64:65]
	v_pk_mul_f32 v[232:233], v[16:17], v[64:65]
	v_pk_mul_f32 v[248:249], v[32:33], v[64:65]
	v_pk_mul_f32 v[250:251], v[48:49], v[64:65]
	v_pk_fma_f32 v[2:3], v[152:153], v[98:99], v[2:3] op_sel_hi:[0,1,1] neg_lo:[1,0,0] neg_hi:[1,0,0]
	v_pk_fma_f32 v[18:19], v[154:155], v[98:99], v[18:19] op_sel_hi:[0,1,1] neg_lo:[1,0,0] neg_hi:[1,0,0]
	v_pk_fma_f32 v[34:35], v[156:157], v[98:99], v[34:35] op_sel_hi:[0,1,1] neg_lo:[1,0,0] neg_hi:[1,0,0]
	v_pk_fma_f32 v[50:51], v[158:159], v[98:99], v[50:51] op_sel_hi:[0,1,1] neg_lo:[1,0,0] neg_hi:[1,0,0]
	v_pk_fma_f32 v[230:231], v[2:3], v[66:67], v[230:231]
	v_pk_fma_f32 v[232:233], v[18:19], v[66:67], v[232:233]
	v_pk_fma_f32 v[248:249], v[34:35], v[66:67], v[248:249]
	v_pk_fma_f32 v[250:251], v[50:51], v[66:67], v[250:251]
	v_pk_fma_f32 v[4:5], v[152:153], v[100:101], v[4:5] op_sel_hi:[0,1,1] neg_lo:[1,0,0] neg_hi:[1,0,0]
	v_pk_fma_f32 v[20:21], v[154:155], v[100:101], v[20:21] op_sel_hi:[0,1,1] neg_lo:[1,0,0] neg_hi:[1,0,0]
	v_pk_fma_f32 v[36:37], v[156:157], v[100:101], v[36:37] op_sel_hi:[0,1,1] neg_lo:[1,0,0] neg_hi:[1,0,0]
	v_pk_fma_f32 v[52:53], v[158:159], v[100:101], v[52:53] op_sel_hi:[0,1,1] neg_lo:[1,0,0] neg_hi:[1,0,0]
	v_pk_fma_f32 v[230:231], v[4:5], v[68:69], v[230:231]
	v_pk_fma_f32 v[232:233], v[20:21], v[68:69], v[232:233]
	v_pk_fma_f32 v[248:249], v[36:37], v[68:69], v[248:249]
	v_pk_fma_f32 v[250:251], v[52:53], v[68:69], v[250:251]
	v_pk_fma_f32 v[6:7], v[152:153], v[102:103], v[6:7] op_sel_hi:[0,1,1] neg_lo:[1,0,0] neg_hi:[1,0,0]
	v_pk_fma_f32 v[22:23], v[154:155], v[102:103], v[22:23] op_sel_hi:[0,1,1] neg_lo:[1,0,0] neg_hi:[1,0,0]
	v_pk_fma_f32 v[38:39], v[156:157], v[102:103], v[38:39] op_sel_hi:[0,1,1] neg_lo:[1,0,0] neg_hi:[1,0,0]
	v_pk_fma_f32 v[54:55], v[158:159], v[102:103], v[54:55] op_sel_hi:[0,1,1] neg_lo:[1,0,0] neg_hi:[1,0,0]
	v_pk_fma_f32 v[230:231], v[6:7], v[70:71], v[230:231]
	v_pk_fma_f32 v[232:233], v[22:23], v[70:71], v[232:233]
	v_pk_fma_f32 v[248:249], v[38:39], v[70:71], v[248:249]
	v_pk_fma_f32 v[250:251], v[54:55], v[70:71], v[250:251]
	v_pk_fma_f32 v[8:9], v[152:153], v[104:105], v[8:9] op_sel_hi:[0,1,1] neg_lo:[1,0,0] neg_hi:[1,0,0]
	v_pk_fma_f32 v[24:25], v[154:155], v[104:105], v[24:25] op_sel_hi:[0,1,1] neg_lo:[1,0,0] neg_hi:[1,0,0]
	v_pk_fma_f32 v[40:41], v[156:157], v[104:105], v[40:41] op_sel_hi:[0,1,1] neg_lo:[1,0,0] neg_hi:[1,0,0]
	v_pk_fma_f32 v[56:57], v[158:159], v[104:105], v[56:57] op_sel_hi:[0,1,1] neg_lo:[1,0,0] neg_hi:[1,0,0]
	v_pk_fma_f32 v[230:231], v[8:9], v[72:73], v[230:231]
	v_pk_fma_f32 v[232:233], v[24:25], v[72:73], v[232:233]
	v_pk_fma_f32 v[248:249], v[40:41], v[72:73], v[248:249]
	v_pk_fma_f32 v[250:251], v[56:57], v[72:73], v[250:251]
	v_pk_fma_f32 v[10:11], v[152:153], v[106:107], v[10:11] op_sel_hi:[0,1,1] neg_lo:[1,0,0] neg_hi:[1,0,0]
	v_pk_fma_f32 v[26:27], v[154:155], v[106:107], v[26:27] op_sel_hi:[0,1,1] neg_lo:[1,0,0] neg_hi:[1,0,0]
	v_pk_fma_f32 v[42:43], v[156:157], v[106:107], v[42:43] op_sel_hi:[0,1,1] neg_lo:[1,0,0] neg_hi:[1,0,0]
	v_pk_fma_f32 v[58:59], v[158:159], v[106:107], v[58:59] op_sel_hi:[0,1,1] neg_lo:[1,0,0] neg_hi:[1,0,0]
	v_pk_fma_f32 v[230:231], v[10:11], v[74:75], v[230:231]
	v_pk_fma_f32 v[232:233], v[26:27], v[74:75], v[232:233]
	v_pk_fma_f32 v[248:249], v[42:43], v[74:75], v[248:249]
	v_pk_fma_f32 v[250:251], v[58:59], v[74:75], v[250:251]
	v_pk_fma_f32 v[12:13], v[152:153], v[108:109], v[12:13] op_sel_hi:[0,1,1] neg_lo:[1,0,0] neg_hi:[1,0,0]
	v_pk_fma_f32 v[28:29], v[154:155], v[108:109], v[28:29] op_sel_hi:[0,1,1] neg_lo:[1,0,0] neg_hi:[1,0,0]
	v_pk_fma_f32 v[44:45], v[156:157], v[108:109], v[44:45] op_sel_hi:[0,1,1] neg_lo:[1,0,0] neg_hi:[1,0,0]
	v_pk_fma_f32 v[60:61], v[158:159], v[108:109], v[60:61] op_sel_hi:[0,1,1] neg_lo:[1,0,0] neg_hi:[1,0,0]
	v_pk_fma_f32 v[230:231], v[12:13], v[76:77], v[230:231]
	v_pk_fma_f32 v[232:233], v[28:29], v[76:77], v[232:233]
	v_pk_fma_f32 v[248:249], v[44:45], v[76:77], v[248:249]
	v_pk_fma_f32 v[250:251], v[60:61], v[76:77], v[250:251]
	v_pk_fma_f32 v[14:15], v[152:153], v[110:111], v[14:15] op_sel_hi:[0,1,1] neg_lo:[1,0,0] neg_hi:[1,0,0]
	v_pk_fma_f32 v[30:31], v[154:155], v[110:111], v[30:31] op_sel_hi:[0,1,1] neg_lo:[1,0,0] neg_hi:[1,0,0]
	v_pk_fma_f32 v[46:47], v[156:157], v[110:111], v[46:47] op_sel_hi:[0,1,1] neg_lo:[1,0,0] neg_hi:[1,0,0]
	v_pk_fma_f32 v[62:63], v[158:159], v[110:111], v[62:63] op_sel_hi:[0,1,1] neg_lo:[1,0,0] neg_hi:[1,0,0]
	v_pk_fma_f32 v[230:231], v[14:15], v[78:79], v[230:231]
	v_pk_fma_f32 v[232:233], v[30:31], v[78:79], v[232:233]
	v_pk_fma_f32 v[248:249], v[46:47], v[78:79], v[248:249]
	v_pk_fma_f32 v[250:251], v[62:63], v[78:79], v[250:251]
